# GEMM-in skinny slab loop (sample rows): the 22 loads trickled between MFMAs behind 9 full drains are issued up front (base+imm addressing, pool = the former K-step 1..3 address registers), counted vmc
# speedup vs baseline: 1.0102x; 1.0102x over previous
; __device__ __forceinline__ f32x4 mfma16(bf16x8 a, bf16x8 b, f32x4 c) { return __builtin_amdgcn_mfma_f32_16x16x32_bf16(a, b, c, 0, 0, 0); }
; template <int RT, class Epi>
; __device__ __forceinline__ void skinny_gemm(const bf16* A, size_t lda, const bf16* Bt, int K, int N, const Epi& epi, int wg, int wg_first, int wg_count, int tid, LAS unsigned char* lds) {
;     ...
;         const bf16* ap = A + (size_t)(r0 + c) * lda + (size_t)w * (K / 8) + 8 * g;
;         const bf16* bp = Bt + (size_t)(n0 + c) * K + (size_t)w * (K / 8) + 8 * g;
; #pragma unroll 4
;         for (int ks = 0; ks < ksteps; ++ks) {
;             bf16x8 af[RT], bfr[2];
; #pragma unroll
;             for (int rt = 0; rt < RT; ++rt) af[rt] = *(const bf16x8*)(ap + (size_t)(16 * rt) * lda + 32 * ks);
;             bfr[0] = *(const bf16x8*)(bp + 32 * ks); bfr[1] = *(const bf16x8*)(bp + (size_t)16 * K + 32 * ks);
; #pragma unroll
;             for (int rt = 0; rt < RT; ++rt) { acc[rt][0] = mfma16(af[rt], bfr[0], acc[rt][0]); acc[rt][1] = mfma16(af[rt], bfr[1], acc[rt][1]); }
;         }
.LBB0_261:
	v_add_u32_e32 v10, s0, v149
	global_load_dwordx4 v[0:3], v[8:9], off
	global_load_dwordx4 v[4:7], v[90:91], off
	v_lshlrev_b64 v[12:13], 11, v[10:11]
	global_load_dwordx4 v[16:19], v[92:93], off
	global_load_dwordx4 v[20:23], v[94:95], off
	global_load_dwordx4 v[24:27], v[96:97], off
	global_load_dwordx4 v[28:31], v[98:99], off
	global_load_dwordx4 v[58:61], v[100:101], off
	global_load_dwordx4 v[66:69], v[102:103], off
	v_lshl_add_u64 v[32:33], v[88:89], 0, v[12:13]
	v_add_co_u32_e32 v56, vcc, 0x8000, v32
	global_load_dwordx4 v[12:15], v[32:33], off
	s_nop 0
	v_addc_co_u32_e32 v57, vcc, 0, v33, vcc
	global_load_dwordx4 v[78:81], v[56:57], off
	global_load_dwordx4 v[82:85], v[90:91], off offset:64
	global_load_dwordx4 v[168:171], v[92:93], off offset:64
	global_load_dwordx4 v[172:175], v[94:95], off offset:64
	global_load_dwordx4 v[188:191], v[96:97], off offset:64
	global_load_dwordx4 v[192:195], v[98:99], off offset:64
	global_load_dwordx4 v[196:199], v[100:101], off offset:64
	global_load_dwordx4 v[200:203], v[102:103], off offset:64
	global_load_dwordx4 v[208:211], v[102:103], off offset:128
	v_add_u32_e32 v150, 0x3800, v158
	s_add_i32 s1, s1, s2
	v_add_u32_e32 v10, s0, v156
	s_add_i32 s0, s0, s3
	s_cmpk_lt_i32 s1, 0x188
	global_load_dwordx4 v[104:107], v[56:57], off offset:128
	global_load_dwordx4 v[108:111], v[8:9], off offset:64
	global_load_dwordx4 v[112:115], v[32:33], off offset:64
	global_load_dwordx4 v[116:119], v[56:57], off offset:64
	global_load_dwordx4 v[120:123], v[8:9], off offset:128
	global_load_dwordx4 v[124:127], v[92:93], off offset:128
	global_load_dwordx4 v[128:131], v[96:97], off offset:128
	global_load_dwordx4 v[132:135], v[90:91], off offset:128
	global_load_dwordx4 v[136:139], v[100:101], off offset:128
	global_load_dwordx4 v[140:143], v[32:33], off offset:128
	global_load_dwordx4 v[216:219], v[94:95], off offset:128
	global_load_dwordx4 v[220:223], v[98:99], off offset:128
	global_load_dwordx4 v[224:227], v[56:57], off offset:192
	global_load_dwordx4 v[228:231], v[8:9], off offset:192
	global_load_dwordx4 v[232:235], v[90:91], off offset:192
	global_load_dwordx4 v[236:239], v[92:93], off offset:192
	global_load_dwordx4 v[240:243], v[32:33], off offset:192
	global_load_dwordx4 v[244:247], v[96:97], off offset:192
	global_load_dwordx4 v[248:251], v[94:95], off offset:192
	global_load_dwordx4 v[152:155], v[98:99], off offset:192
	s_waitcnt vmcnt(20) lgkmcnt(0)
	v_mfma_f32_16x16x32_bf16 v[34:37], v[0:3], v[12:15], 0
	s_nop 0
	v_mfma_f32_16x16x32_bf16 v[38:41], v[4:7], v[12:15], 0
	v_mfma_f32_16x16x32_bf16 v[42:45], v[16:19], v[12:15], 0
	v_mfma_f32_16x16x32_bf16 v[46:49], v[20:23], v[12:15], 0
	v_mfma_f32_16x16x32_bf16 v[50:53], v[24:27], v[12:15], 0
	v_mfma_f32_16x16x32_bf16 v[62:65], v[28:31], v[12:15], 0
	v_mfma_f32_16x16x32_bf16 v[70:73], v[58:61], v[12:15], 0
	v_mfma_f32_16x16x32_bf16 v[74:77], v[66:69], v[12:15], 0
	v_mfma_f32_16x16x32_bf16 v[12:15], v[16:19], v[78:81], 0
	v_mfma_f32_16x16x32_bf16 v[16:19], v[20:23], v[78:81], 0
	v_mfma_f32_16x16x32_bf16 v[20:23], v[24:27], v[78:81], 0
	v_mfma_f32_16x16x32_bf16 v[24:27], v[28:31], v[78:81], 0
	v_mfma_f32_16x16x32_bf16 v[28:31], v[58:61], v[78:81], 0
	s_nop 0
	v_mfma_f32_16x16x32_bf16 v[0:3], v[0:3], v[78:81], 0
	v_mfma_f32_16x16x32_bf16 v[4:7], v[4:7], v[78:81], 0
	v_mfma_f32_16x16x32_bf16 v[66:69], v[66:69], v[78:81], 0
	s_nop 0
	s_waitcnt vmcnt(17) lgkmcnt(0)
	v_mov_b32_e32 v212, v104
	v_mov_b32_e32 v213, v105
	v_mov_b32_e32 v214, v106
	v_mov_b32_e32 v215, v107
	v_mov_b32_e32 v58, v108
	v_mov_b32_e32 v59, v109
	v_mov_b32_e32 v60, v110
	v_mov_b32_e32 v61, v111
	v_mov_b32_e32 v78, v112
	v_mov_b32_e32 v79, v113
	v_mov_b32_e32 v80, v114
	v_mov_b32_e32 v81, v115
	s_nop 1
	global_load_dwordx4 v[104:107], v[100:101], off offset:192
	global_load_dwordx4 v[108:111], v[102:103], off offset:192
	v_mfma_f32_16x16x32_bf16 v[34:37], v[58:61], v[78:81], v[34:37]
	v_mfma_f32_16x16x32_bf16 v[38:41], v[82:85], v[78:81], v[38:41]
	v_mfma_f32_16x16x32_bf16 v[42:45], v[168:171], v[78:81], v[42:45]
	v_mfma_f32_16x16x32_bf16 v[46:49], v[172:175], v[78:81], v[46:49]
	v_mfma_f32_16x16x32_bf16 v[50:53], v[188:191], v[78:81], v[50:53]
	v_mfma_f32_16x16x32_bf16 v[62:65], v[192:195], v[78:81], v[62:65]
	v_mfma_f32_16x16x32_bf16 v[70:73], v[196:199], v[78:81], v[70:73]
	v_mfma_f32_16x16x32_bf16 v[74:77], v[200:203], v[78:81], v[74:77]
	s_nop 0
	s_waitcnt vmcnt(18) lgkmcnt(0)
	v_mov_b32_e32 v78, v116
	v_mov_b32_e32 v79, v117
	v_mov_b32_e32 v80, v118
	v_mov_b32_e32 v81, v119
	s_nop 1
	v_mfma_f32_16x16x32_bf16 v[0:3], v[58:61], v[78:81], v[0:3]
	s_nop 0
	v_mfma_f32_16x16x32_bf16 v[4:7], v[82:85], v[78:81], v[4:7]
	v_mfma_f32_16x16x32_bf16 v[12:15], v[168:171], v[78:81], v[12:15]
	s_nop 0
	v_mfma_f32_16x16x32_bf16 v[16:19], v[172:175], v[78:81], v[16:19]
	v_mfma_f32_16x16x32_bf16 v[20:23], v[188:191], v[78:81], v[20:23]
	s_nop 0
	v_mfma_f32_16x16x32_bf16 v[24:27], v[192:195], v[78:81], v[24:27]
	v_mfma_f32_16x16x32_bf16 v[28:31], v[196:199], v[78:81], v[28:31]
	v_mfma_f32_16x16x32_bf16 v[84:87], v[200:203], v[78:81], v[66:69]
	s_nop 0
	s_nop 0
	s_nop 0
	s_nop 0
	s_waitcnt vmcnt(12) lgkmcnt(0)
	v_mov_b32_e32 v58, v120
	v_mov_b32_e32 v59, v121
	v_mov_b32_e32 v60, v122
	v_mov_b32_e32 v61, v123
	v_mov_b32_e32 v168, v124
	v_mov_b32_e32 v169, v125
	v_mov_b32_e32 v170, v126
	v_mov_b32_e32 v171, v127
	v_mov_b32_e32 v188, v128
	v_mov_b32_e32 v189, v129
	v_mov_b32_e32 v190, v130
	v_mov_b32_e32 v191, v131
	v_mov_b32_e32 v78, v132
	v_mov_b32_e32 v79, v133
	v_mov_b32_e32 v80, v134
	v_mov_b32_e32 v81, v135
	v_mov_b32_e32 v200, v136
	v_mov_b32_e32 v201, v137
	v_mov_b32_e32 v202, v138
	v_mov_b32_e32 v203, v139
	v_mov_b32_e32 v66, v140
	v_mov_b32_e32 v67, v141
	v_mov_b32_e32 v68, v142
	v_mov_b32_e32 v69, v143
	s_nop 1
	v_mfma_f32_16x16x32_bf16 v[172:175], v[168:171], v[66:69], v[42:45]
	s_nop 2
	s_nop 0
	v_mfma_f32_16x16x32_bf16 v[192:195], v[188:191], v[66:69], v[50:53]
	s_nop 2
	s_nop 0
	v_mfma_f32_16x16x32_bf16 v[34:37], v[58:61], v[66:69], v[34:37]
	v_mfma_f32_16x16x32_bf16 v[38:41], v[78:81], v[66:69], v[38:41]
	s_waitcnt vmcnt(10) lgkmcnt(0)
; #define LAS __attribute__((address_space(3)))
; __device__ __forceinline__ f32x4 mfma16(bf16x8 a, bf16x8 b, f32x4 c) { return __builtin_amdgcn_mfma_f32_16x16x32_bf16(a, b, c, 0, 0, 0); }
; __device__ __forceinline__ void sync_threads() { __syncthreads(); }
; template <int RT, class Epi>
; __device__ __forceinline__ void skinny_gemm(const bf16* A, size_t lda, const bf16* Bt, int K, int N, const Epi& epi, int wg, int wg_first, int wg_count, int tid, LAS unsigned char* lds) {
;     ...
; #pragma unroll 4
;         for (int ks = 0; ks < ksteps; ++ks) {
;             bf16x8 af[RT], bfr[2];
; #pragma unroll
;             for (int rt = 0; rt < RT; ++rt) af[rt] = *(const bf16x8*)(ap + (size_t)(16 * rt) * lda + 32 * ks);
;             bfr[0] = *(const bf16x8*)(bp + 32 * ks); bfr[1] = *(const bf16x8*)(bp + (size_t)16 * K + 32 * ks);
; #pragma unroll
;             for (int rt = 0; rt < RT; ++rt) { acc[rt][0] = mfma16(af[rt], bfr[0], acc[rt][0]); acc[rt][1] = mfma16(af[rt], bfr[1], acc[rt][1]); }
;         }
;         LAS float* part = (LAS float*)(lds + w * SK_PART);
; #pragma unroll
;         for (int rt = 0; rt < RT; ++rt)
; #pragma unroll
;             for (int nt = 0; nt < 2; ++nt)
; #pragma unroll
;                 for (int r = 0; r < 4; ++r) part[(16 * rt + 4 * g + r) * 32 + 16 * nt + c] = acc[rt][nt][r];
;         sync_threads();
	v_mov_b32_e32 v42, v216
	v_mov_b32_e32 v43, v217
	v_mov_b32_e32 v44, v218
	v_mov_b32_e32 v45, v219
	v_mov_b32_e32 v50, v220
	v_mov_b32_e32 v51, v221
	v_mov_b32_e32 v52, v222
	v_mov_b32_e32 v53, v223
	s_nop 1
	v_mfma_f32_16x16x32_bf16 v[46:49], v[42:45], v[66:69], v[46:49]
	v_mfma_f32_16x16x32_bf16 v[196:199], v[50:53], v[66:69], v[62:65]
	v_mfma_f32_16x16x32_bf16 v[204:207], v[200:203], v[66:69], v[70:73]
	v_mfma_f32_16x16x32_bf16 v[72:75], v[208:211], v[66:69], v[74:77]
	v_mfma_f32_16x16x32_bf16 v[64:67], v[58:61], v[212:215], v[0:3]
	s_nop 0
	v_mfma_f32_16x16x32_bf16 v[68:71], v[78:81], v[212:215], v[4:7]
	v_mfma_f32_16x16x32_bf16 v[76:79], v[168:171], v[212:215], v[12:15]
	s_nop 0
	v_mfma_f32_16x16x32_bf16 v[60:63], v[188:191], v[212:215], v[20:23]
	s_nop 0
	v_mfma_f32_16x16x32_bf16 v[0:3], v[200:203], v[212:215], v[28:31]
	s_nop 0
	v_mfma_f32_16x16x32_bf16 v[80:83], v[42:45], v[212:215], v[16:19]
	s_nop 2
	s_nop 0
	v_mfma_f32_16x16x32_bf16 v[4:7], v[208:211], v[212:215], v[84:87]
	s_nop 0
	s_waitcnt vmcnt(4) lgkmcnt(0)
	v_mov_b32_e32 v56, v224
	v_mov_b32_e32 v57, v225
	v_mov_b32_e32 v58, v226
	v_mov_b32_e32 v59, v227
	v_mov_b32_e32 v168, v228
	v_mov_b32_e32 v169, v229
	v_mov_b32_e32 v170, v230
	v_mov_b32_e32 v171, v231
	v_mov_b32_e32 v188, v232
	v_mov_b32_e32 v189, v233
	v_mov_b32_e32 v190, v234
	v_mov_b32_e32 v191, v235
	v_mov_b32_e32 v200, v236
	v_mov_b32_e32 v201, v237
	v_mov_b32_e32 v202, v238
	v_mov_b32_e32 v203, v239
	v_mov_b32_e32 v16, v240
	v_mov_b32_e32 v17, v241
	v_mov_b32_e32 v18, v242
	v_mov_b32_e32 v19, v243
	v_mov_b32_e32 v208, v244
	v_mov_b32_e32 v209, v245
	v_mov_b32_e32 v210, v246
	v_mov_b32_e32 v211, v247
	s_nop 1
	v_mfma_f32_16x16x32_bf16 v[12:15], v[168:171], v[16:19], v[34:37]
	v_mfma_f32_16x16x32_bf16 v[40:43], v[188:191], v[16:19], v[38:41]
	v_mfma_f32_16x16x32_bf16 v[36:39], v[200:203], v[16:19], v[172:175]
	s_nop 2
	s_nop 0
	v_mfma_f32_16x16x32_bf16 v[52:55], v[50:53], v[212:215], v[24:27]
	v_mfma_f32_16x16x32_bf16 v[28:31], v[208:211], v[16:19], v[192:195]
	s_nop 2
	s_nop 0
	s_waitcnt vmcnt(2) lgkmcnt(0)
	v_mov_b32_e32 v172, v248
	v_mov_b32_e32 v173, v249
	v_mov_b32_e32 v174, v250
	v_mov_b32_e32 v175, v251
	v_mov_b32_e32 v192, v152
	v_mov_b32_e32 v193, v153
	v_mov_b32_e32 v194, v154
	v_mov_b32_e32 v195, v155
	s_nop 1
	v_mfma_f32_16x16x32_bf16 v[32:35], v[172:175], v[16:19], v[46:49]
	s_nop 2
	s_nop 0
	s_nop 0
	v_mfma_f32_16x16x32_bf16 v[84:87], v[168:171], v[56:59], v[64:67]
	v_mfma_f32_16x16x32_bf16 v[24:27], v[192:195], v[16:19], v[196:199]
	s_waitcnt vmcnt(0) lgkmcnt(0)
	v_mov_b32_e32 v48, v104
	v_mov_b32_e32 v49, v105
	v_mov_b32_e32 v50, v106
	v_mov_b32_e32 v51, v107
	v_mov_b32_e32 v44, v108
	v_mov_b32_e32 v45, v109
	v_mov_b32_e32 v46, v110
	v_mov_b32_e32 v47, v111
	s_nop 1
	v_mfma_f32_16x16x32_bf16 v[20:23], v[48:51], v[16:19], v[204:207]
	v_mfma_f32_16x16x32_bf16 v[16:19], v[44:47], v[16:19], v[72:75]
	v_mfma_f32_16x16x32_bf16 v[64:67], v[172:175], v[56:59], v[80:83]
	v_mfma_f32_16x16x32_bf16 v[60:63], v[208:211], v[56:59], v[60:63]
	s_nop 1
	v_add_u32_e32 v80, 0x1800, v158
	v_add_u32_e32 v81, 0x2000, v158
	v_add_u32_e32 v82, 0x2800, v158
	v_mfma_f32_16x16x32_bf16 v[52:55], v[192:195], v[56:59], v[52:55]
	v_add_u32_e32 v83, 0x3000, v158
	v_mfma_f32_16x16x32_bf16 v[0:3], v[48:51], v[56:59], v[0:3]
	v_mfma_f32_16x16x32_bf16 v[4:7], v[44:47], v[56:59], v[4:7]
	v_mfma_f32_16x16x32_bf16 v[72:75], v[188:191], v[56:59], v[68:71]
	v_mfma_f32_16x16x32_bf16 v[68:71], v[200:203], v[56:59], v[76:79]
	s_nop 2
	v_add_u32_e32 v78, 0x800, v158
	v_add_u32_e32 v79, 0x1000, v158
	ds_write2_b32 v158, v12, v84 offset1:16
	ds_write2_b32 v158, v13, v85 offset0:32 offset1:48
	ds_write2_b32 v158, v14, v86 offset0:64 offset1:80
	ds_write2_b32 v158, v15, v87 offset0:96 offset1:112
	ds_write2_b32 v78, v40, v72 offset1:16
	ds_write2_b32 v78, v41, v73 offset0:32 offset1:48
	ds_write2_b32 v78, v42, v74 offset0:64 offset1:80
	ds_write2_b32 v78, v43, v75 offset0:96 offset1:112
	ds_write2_b32 v79, v36, v68 offset1:16
	ds_write2_b32 v79, v37, v69 offset0:32 offset1:48
	ds_write2_b32 v79, v38, v70 offset0:64 offset1:80
	ds_write2_b32 v79, v39, v71 offset0:96 offset1:112
	ds_write2_b32 v80, v32, v64 offset1:16
	ds_write2_b32 v80, v33, v65 offset0:32 offset1:48
	ds_write2_b32 v80, v34, v66 offset0:64 offset1:80
	ds_write2_b32 v80, v35, v67 offset0:96 offset1:112
	ds_write2_b32 v81, v28, v60 offset1:16
	ds_write2_b32 v81, v29, v61 offset0:32 offset1:48
	ds_write2_b32 v81, v30, v62 offset0:64 offset1:80
	ds_write2_b32 v81, v31, v63 offset0:96 offset1:112
	ds_write2_b32 v82, v24, v52 offset1:16
	ds_write2_b32 v82, v25, v53 offset0:32 offset1:48
	ds_write2_b32 v82, v26, v54 offset0:64 offset1:80
	ds_write2_b32 v82, v27, v55 offset0:96 offset1:112
	ds_write2_b32 v83, v20, v0 offset1:16
	ds_write2_b32 v83, v21, v1 offset0:32 offset1:48
	ds_write2_b32 v83, v22, v2 offset0:64 offset1:80
	ds_write2_b32 v83, v23, v3 offset0:96 offset1:112
	ds_write2_b32 v150, v16, v4 offset1:16
	ds_write2_b32 v150, v17, v5 offset0:32 offset1:48
	ds_write2_b32 v150, v18, v6 offset0:64 offset1:80
	ds_write2_b32 v150, v19, v7 offset0:96 offset1:112
	s_waitcnt lgkmcnt(0)
	s_barrier
; #define LAS __attribute__((address_space(3)))
; __device__ __forceinline__ void sync_threads() { __syncthreads(); }
; template <int RT, class Epi>
; __device__ __forceinline__ void skinny_gemm(const bf16* A, size_t lda, const bf16* Bt, int K, int N, const Epi& epi, int wg, int wg_first, int wg_count, int tid, LAS unsigned char* lds) {
;     ...
;         sync_threads();
;         if (RT == 8 || tid < 64 * RT) {
;             const int row = tid >> 2, c8 = (tid & 3) * 8;
;             f32x4 v0 = (f32x4){0.f, 0.f, 0.f, 0.f}, v1 = (f32x4){0.f, 0.f, 0.f, 0.f};
; #pragma unroll
;             for (int ww = 0; ww < 8; ++ww) { const LAS float* pp = (const LAS float*)(lds + ww * SK_PART) + row * 32 + c8; v0 = v0 + *(const LAS f32x4*)pp; v1 = v1 + *(const LAS f32x4*)(pp + 4); }
;             epi(r0 + row, n0 + c8, v0, v1);
;         }
;         sync_threads();
;     }
; }
	ds_read_b128 v[0:3], v157
	ds_read_b128 v[4:7], v157 offset:16
	ds_read_b128 v[12:15], v157 offset:16384
	ds_read_b128 v[16:19], v157 offset:16400
	ds_read_b128 v[20:23], v157 offset:32768
	ds_read_b128 v[24:27], v157 offset:32784
	ds_read_b128 v[28:31], v157 offset:49152
	ds_read_b128 v[32:35], v157 offset:49168
	ds_read_b128 v[36:39], v159
	ds_read_b128 v[40:43], v160
	ds_read_b128 v[44:47], v161
	ds_read_b128 v[48:51], v162
	ds_read_b128 v[52:55], v163
	ds_read_b128 v[56:59], v164
	ds_read_b128 v[60:63], v165
	ds_read_b128 v[64:67], v166
	s_waitcnt lgkmcnt(14)
	v_pk_add_f32 v[2:3], v[2:3], 0 op_sel_hi:[1,0]
	v_pk_add_f32 v[0:1], v[0:1], 0 op_sel_hi:[1,0]
	v_pk_add_f32 v[6:7], v[6:7], 0 op_sel_hi:[1,0]
	v_pk_add_f32 v[4:5], v[4:5], 0 op_sel_hi:[1,0]
	s_waitcnt lgkmcnt(13)
	v_pk_add_f32 v[2:3], v[2:3], v[14:15]
	v_pk_add_f32 v[0:1], v[0:1], v[12:13]
	s_waitcnt lgkmcnt(12)
	v_pk_add_f32 v[6:7], v[6:7], v[18:19]
	v_pk_add_f32 v[4:5], v[4:5], v[16:17]
	s_waitcnt lgkmcnt(11)
	v_pk_add_f32 v[2:3], v[2:3], v[22:23]
	v_pk_add_f32 v[0:1], v[0:1], v[20:21]
	s_waitcnt lgkmcnt(10)
	v_pk_add_f32 v[6:7], v[6:7], v[26:27]
	v_pk_add_f32 v[4:5], v[4:5], v[24:25]
	s_waitcnt lgkmcnt(9)
	v_pk_add_f32 v[2:3], v[2:3], v[30:31]
	v_pk_add_f32 v[0:1], v[0:1], v[28:29]
	s_waitcnt lgkmcnt(8)
	v_pk_add_f32 v[6:7], v[6:7], v[34:35]
	v_pk_add_f32 v[4:5], v[4:5], v[32:33]
	s_waitcnt lgkmcnt(7)
	v_pk_add_f32 v[2:3], v[2:3], v[38:39]
	v_pk_add_f32 v[0:1], v[0:1], v[36:37]
	s_waitcnt lgkmcnt(6)
	v_pk_add_f32 v[6:7], v[6:7], v[42:43]
	v_pk_add_f32 v[4:5], v[4:5], v[40:41]
	s_waitcnt lgkmcnt(5)
	v_pk_add_f32 v[2:3], v[2:3], v[46:47]
	v_pk_add_f32 v[0:1], v[0:1], v[44:45]
	s_waitcnt lgkmcnt(4)
	v_pk_add_f32 v[6:7], v[6:7], v[50:51]
	v_pk_add_f32 v[4:5], v[4:5], v[48:49]
	s_waitcnt lgkmcnt(3)
	v_pk_add_f32 v[2:3], v[2:3], v[54:55]
	v_pk_add_f32 v[0:1], v[0:1], v[52:53]
	v_lshl_add_u64 v[76:77], v[10:11], 1, v[146:147]
	s_waitcnt lgkmcnt(2)
	v_pk_add_f32 v[6:7], v[6:7], v[58:59]
	v_pk_add_f32 v[4:5], v[4:5], v[56:57]
	s_waitcnt lgkmcnt(1)
	v_pk_add_f32 v[2:3], v[2:3], v[62:63]
	v_pk_add_f32 v[0:1], v[0:1], v[60:61]
	s_waitcnt lgkmcnt(0)
	v_pk_add_f32 v[6:7], v[6:7], v[66:67]
	v_pk_add_f32 v[4:5], v[4:5], v[64:65]
	v_cvt_pk_bf16_f32 v0, v0, v1
	v_cvt_pk_bf16_f32 v1, v2, v3
	v_cvt_pk_bf16_f32 v3, v6, v7
	s_nop 0
	v_cvt_pk_bf16_f32 v2, v4, v5
	global_store_dwordx4 v[76:77], v[0:3], off
	s_waitcnt lgkmcnt(0)
	s_barrier
	s_cbranch_scc1 .LBB0_261
